# dead-instruction trim: three overwritten v_mov at the top of the attention B unit prologue removed
# speedup vs baseline: 1.0026x; 1.0009x over previous
.LBB0_380:
	s_and_b32 s30, s28, 7
	s_mul_i32 s4, s30, 0x201
	s_mov_b64 s[12:13], 0
	s_barrier
	v_mul_hi_u32 v3, v215, s21
	v_lshrrev_b32_e32 v3, 9, v3
	v_mad_u32_u24 v22, v3, 48, v111
	v_sub_u32_e32 v4, v110, v3
	v_mad_u32_u24 v4, v3, s22, v4
	v_med3_i32 v4, v4, s23, v114
	v_add_u32_e32 v4, s4, v4
	v_ashrrev_i32_e32 v5, 31, v4
	v_lshl_add_u64 v[4:5], v[4:5], 2, s[66:67]
	global_load_dword v16, v[4:5], off offset:1024
	v_add_u32_e32 v2, 0x200, v215
	v_mul_hi_u32 v3, v2, s21
	v_lshrrev_b32_e32 v3, 9, v3
	v_mad_u32_u24 v23, v3, 48, v111
	v_sub_u32_e32 v6, v110, v3
	v_add_u32_e32 v6, 0xfffffe00, v6
	v_mad_u32_u24 v6, v3, s22, v6
	v_med3_i32 v6, v6, s23, v114
	v_add_u32_e32 v6, s4, v6
	v_ashrrev_i32_e32 v7, 31, v6
	v_lshl_add_u64 v[6:7], v[6:7], 2, s[66:67]
	global_load_dword v17, v[6:7], off offset:1024
	v_add_u32_e32 v2, 0x400, v215
	v_mul_hi_u32 v3, v2, s21
	v_lshrrev_b32_e32 v3, 9, v3
	v_mad_u32_u24 v24, v3, 48, v111
	v_sub_u32_e32 v8, v110, v3
	v_add_u32_e32 v8, 0xfffffc00, v8
	v_mad_u32_u24 v8, v3, s22, v8
	v_med3_i32 v8, v8, s23, v114
	v_add_u32_e32 v8, s4, v8
	v_ashrrev_i32_e32 v9, 31, v8
	v_lshl_add_u64 v[8:9], v[8:9], 2, s[66:67]
	global_load_dword v18, v[8:9], off offset:1024
	v_add_u32_e32 v2, 0x600, v215
	v_mul_hi_u32 v3, v2, s21
	v_lshrrev_b32_e32 v3, 9, v3
	v_mad_u32_u24 v25, v3, 48, v111
	v_sub_u32_e32 v10, v110, v3
	v_add_u32_e32 v10, 0xfffffa00, v10
	v_mad_u32_u24 v10, v3, s22, v10
	v_med3_i32 v10, v10, s23, v114
	v_add_u32_e32 v10, s4, v10
	v_ashrrev_i32_e32 v11, 31, v10
	v_lshl_add_u64 v[10:11], v[10:11], 2, s[66:67]
	global_load_dword v19, v[10:11], off offset:1024
	v_add_u32_e32 v2, 0x800, v215
	v_mul_hi_u32 v3, v2, s21
	v_lshrrev_b32_e32 v3, 9, v3
	v_mad_u32_u24 v26, v3, 48, v111
	v_sub_u32_e32 v12, v110, v3
	v_add_u32_e32 v12, 0xfffff800, v12
	v_mad_u32_u24 v12, v3, s22, v12
	v_med3_i32 v12, v12, s23, v114
	v_add_u32_e32 v12, s4, v12
	v_ashrrev_i32_e32 v13, 31, v12
	v_lshl_add_u64 v[12:13], v[12:13], 2, s[66:67]
	global_load_dword v20, v[12:13], off offset:1024
	v_cmp_gt_u32_e32 vcc, 16, v215
	s_and_saveexec_b64 s[12:13], vcc
	v_add_u32_e32 v2, 0xa00, v215
	v_mul_hi_u32 v3, v2, s21
	v_lshrrev_b32_e32 v3, 9, v3
	v_mad_u32_u24 v27, v3, 48, v111
	v_sub_u32_e32 v14, v110, v3
	v_add_u32_e32 v14, 0xfffff600, v14
	v_mad_u32_u24 v14, v3, s22, v14
	v_med3_i32 v14, v14, s23, v114
	v_add_u32_e32 v14, s4, v14
	v_ashrrev_i32_e32 v15, 31, v14
	v_lshl_add_u64 v[14:15], v[14:15], 2, s[66:67]
	global_load_dword v21, v[14:15], off offset:1024
	s_or_b64 exec, exec, s[12:13]
	s_ashr_i32 s13, s28, 7
	s_lshl_b32 s37, s13, 8
	s_lshl_b32 s4, s28, 8
	s_add_i32 s37, s37, s40
	s_lshl_b32 s12, s13, 2
	s_and_b32 s31, s4, 0x7800
	s_ashr_i32 s29, s37, 31
	s_add_u32 s4, s37, s31
	s_addc_u32 s29, s29, 0
	s_mul_i32 s34, s29, 0x1800
	s_mul_hi_u32 s35, s4, 0x1800
	s_add_i32 s35, s35, s34
	s_mul_i32 s34, s4, 0x1800
	s_add_u32 s34, s10, s34
	s_addc_u32 s35, s11, s35
	s_lshl_b32 s36, s30, 7
	s_add_u32 s34, s34, s36
	s_addc_u32 s35, s35, 0
	v_lshl_add_u64 v[0:1], s[34:35], 0, v[132:133]
	v_lshl_add_u64 v[0:1], v[0:1], 0, v[134:135]
	global_load_dwordx4 v[64:67], v[0:1], off offset:3072
	global_load_dwordx4 v[68:71], v[0:1], off offset:3104
	global_load_dwordx4 v[72:75], v[0:1], off offset:3136
	global_load_dwordx4 v[76:79], v[0:1], off offset:3168
	s_mulk_i32 s31, 0x1800
	s_add_u32 s31, s10, s31
	s_addc_u32 s35, s11, 0
	s_add_u32 s31, s31, s36
	s_addc_u32 s35, s35, 0
	s_add_u32 s43, s31, 0x1000
	s_addc_u32 s44, s35, 0
	v_readfirstlane_b32 s34, v215
	s_add_u32 s36, s31, 0x1400
	s_addc_u32 s38, s35, 0
	s_max_i32 s42, s12, 8
	s_lshr_b32 s39, s34, 6
	s_add_i32 s35, s42, -8
	v_lshl_or_b32 v0, s39, 3, v172
	s_add_i32 s31, s12, 4
	v_lshrrev_b32_e32 v2, 1, v0
	s_mul_i32 s54, s35, 0x60000
	s_mul_hi_u32 s45, s35, 0x60000
	v_xor_b32_e32 v2, v2, v215
	s_add_u32 s52, s43, s54
	v_lshlrev_b32_e32 v2, 3, v2
	s_addc_u32 s53, s44, s45
	s_lshl_b32 s34, s39, 10
	v_mul_lo_u32 v3, v0, s18
	v_and_b32_e32 v32, 56, v2
	s_add_i32 s34, s34, 0
	v_or_b32_e32 v98, v32, v3
	s_add_u32 s54, s36, s54
	v_mov_b32_e32 v1, v99
	v_or_b32_e32 v0, v115, v3
	v_lshl_add_u64 v[2:3], v[98:99], 1, s[52:53]
	s_addc_u32 s55, s38, s45
	s_mov_b32 m0, s34
	v_lshl_add_u64 v[4:5], v[0:1], 1, s[54:55]
	s_add_i32 s45, s42, -7
	global_load_lds_dwordx4 v[2:3], off
	s_add_i32 m0, s34, 0x2000
	s_nop 0
	global_load_lds_dwordx4 v[4:5], off
	s_waitcnt vmcnt(6)
	v_mul_f32_e32 v16, 0x3fb8aa3b, v16
	ds_write_b32 v22, v16
	v_mul_f32_e32 v17, 0x3fb8aa3b, v17
	ds_write_b32 v23, v17 offset:2048
	v_mul_f32_e32 v18, 0x3fb8aa3b, v18
	ds_write_b32 v24, v18 offset:4096
	v_mul_f32_e32 v19, 0x3fb8aa3b, v19
	ds_write_b32 v25, v19 offset:6144
	v_mul_f32_e32 v20, 0x3fb8aa3b, v20
	ds_write_b32 v26, v20 offset:8192
	v_cmp_gt_u32_e32 vcc, 16, v215
	s_and_saveexec_b64 s[100:101], vcc
	v_mul_f32_e32 v21, 0x3fb8aa3b, v21
	ds_write_b32 v27, v21 offset:10240
	s_or_b64 exec, exec, s[100:101]
	s_cmp_ge_i32 s45, s31
	s_cbranch_scc1 .LBB0_384
	s_mul_hi_u32 s54, s45, 0x60000
	s_mul_i32 s45, s45, 0x60000
	s_add_u32 s52, s43, s45
	s_addc_u32 s53, s44, s54
	s_add_i32 m0, s34, 0x4000
	v_lshl_add_u64 v[2:3], v[98:99], 1, s[52:53]
	s_add_u32 s52, s36, s45
	s_addc_u32 s53, s38, s54
	global_load_lds_dwordx4 v[2:3], off
	v_lshl_add_u64 v[2:3], v[0:1], 1, s[52:53]
	s_add_i32 m0, s34, 0x6000
	s_nop 0
	global_load_lds_dwordx4 v[2:3], off
